# attention loops: deferred cvt+rowsum into PV MFMA gaps, K-frag prefetch, persistent -m C tuple, saddr DMA
# speedup vs baseline: 1.0218x; 1.0218x over previous
; #define LAS __attribute__((address_space(3)))
; DI void diff_core(unsigned char* smem, const u16* qptr, const u16* kbase, const u16* vtbase, int vld,
;                   int ntb, int ntw, int nvalid, int ks0, const float* lut, int qpos, bool active, bool grpB,
;                   f32x16 (&O)[4], float& l_out) {
;     ...
;   for (int s = 0; s < 4; ++s) qf[s] = *reinterpret_cast<const bf16x8*>(qptr + s * 16);
; #pragma unroll
;   for (int t = 0; t < 4; ++t)
; #pragma unroll
;     for (int e = 0; e < 16; ++e) O[t][e] = 0.f;
;   float m = 0.f, l = 0.f;
;   f32x16 S[2];
;   u32x4 P[4];
; #pragma unroll
;   for (int i = 0; i < 4; ++i) P[i] = (u32x4){0u, 0u, 0u, 0u};
; #pragma unroll
;   for (int kb = 0; kb < 2; ++kb)
; #pragma unroll
;     for (int e = 0; e < 16; ++e) S[kb][e] = 0.f;
;   unsigned ksrc[2], vsrc[2];
; #pragma unroll
;   for (int i = 0; i < 2; ++i) {
;     const int ci = (i * 8 + w) * 64 + lane;
;     const int krow = ci >> 4, kc = (ci & 15) ^ (krow & 15);
;     ksrc[i] = (unsigned)(krow * kld + kc * 8) * 2u;
;     const int vrow = ci >> 3, vc = (ci & 7) ^ ((vrow >> 1) & 7);
;     vsrc[i] = (unsigned)(vrow * vld + vc * 8) * 2u;
;   }
;   auto dma_piece = [&](int t, int slot, int piece) {
;     LAS unsigned char* b = lds + slot * D_SLOT + w * 1024;
;     const char* kt = (const char*)kbase + (size_t)(64 * t) * kld * 2;
;     const char* vt = (const char*)vtbase + (size_t)(64 * t) * 2;
;     if (piece == 0) __builtin_amdgcn_global_load_lds((const unsigned*)(kt + ksrc[0]), (LAS unsigned*)(b), 16, 0, 0);
;     else if (piece == 1) __builtin_amdgcn_global_load_lds((const unsigned*)(kt + ksrc[1]), (LAS unsigned*)(b + 8192), 16, 0, 0);
;     else if (piece == 2) __builtin_amdgcn_global_load_lds((const unsigned*)(vt + vsrc[0]), (LAS unsigned*)(b + 16384), 16, 0, 0);
;     else __builtin_amdgcn_global_load_lds((const unsigned*)(vt + vsrc[1]), (LAS unsigned*)(b + 24576), 16, 0, 0);
;   };
;   auto dma = [&](int t, int slot) { dma_piece(t, slot, 0); dma_piece(t, slot, 1); dma_piece(t, slot, 2); dma_piece(t, slot, 3); };
;     ...
;   asm volatile("s_waitcnt vmcnt(0)" :: "v"(qf[0]), "v"(qf[1]), "v"(qf[2]), "v"(qf[3]) : "memory");
;   dma(0, 0); dma(1 < tlast ? 1 : tlast, 1);
;   if (!grpB) { dma(2 < tlast ? 2 : tlast, 2); asm volatile("s_waitcnt vmcnt(8)" ::: "memory"); }
;   else { asm volatile("s_waitcnt vmcnt(4)" ::: "memory"); }
;   D_BAR;
.LBB0_344:
	s_or_b64 exec, exec, s[0:1]
	s_waitcnt lgkmcnt(0)
	s_barrier
	ds_read_b32 v0, v172
	s_movk_i32 s0, 0xff
	s_waitcnt lgkmcnt(0)
	s_barrier
	v_cmp_lt_i32_e32 vcc, s0, v0
	v_readfirstlane_b32 s6, v0
	s_mov_b64 s[0:1], -1
	s_cbranch_vccnz .LBB0_339
	v_mov_b32_e32 v175, v160
	s_ashr_i32 s62, s6, 1
	s_and_b32 s59, s6, 1
	v_readfirstlane_b32 s56, v175
	s_sub_i32 s0, 0x7f, s62
	s_bfe_u32 s39, s56, 0x20006
	s_or_b32 s57, s59, s33
	s_lshl_b32 s1, s0, 7
	s_lshl_b32 s6, s39, 5
	s_lshl_b32 s0, s0, 1
	v_and_b32_e32 v182, 31, v175
	s_ashr_i32 s64, s56, 8
	s_or_b32 s63, s6, s1
	s_or_b32 s58, s0, 1
	s_lshl_b32 s6, s57, 8
	v_or_b32_e32 v0, s34, v182
	s_add_u32 s14, s36, s6
	v_add_u32_e32 v0, s63, v0
	s_addc_u32 s15, s37, 0
	s_lshl_b32 s0, s57, 22
	s_or_b32 s0, s0, s35
	v_ashrrev_i32_e32 v1, 31, v0
	v_readlane_b32 s40, v255, 0
	s_add_u32 s20, s68, s0
	v_lshlrev_b64 v[164:165], 11, v[0:1]
	v_readlane_b32 s52, v255, 12
	v_readlane_b32 s53, v255, 13
	s_addc_u32 s21, s69, 0
	s_lshl_b32 s0, s64, 6
	v_lshl_add_u64 v[0:1], s[52:53], 0, v[164:165]
	v_bfe_u32 v174, v175, 5, 1
	v_lshl_add_u64 v[0:1], v[0:1], 0, s[6:7]
	s_ashr_i32 s1, s0, 31
	v_lshl_add_u64 v[0:1], s[0:1], 1, v[0:1]
	v_lshlrev_b32_e32 v162, 4, v174
	v_lshl_add_u64 v[2:3], v[0:1], 0, v[162:163]
	v_mov_b32_e32 v0, v160
	global_load_dwordx4 v[128:131], v[2:3], off
	global_load_dwordx4 v[132:135], v[2:3], off offset:32
	global_load_dwordx4 v[136:139], v[2:3], off offset:64
	global_load_dwordx4 v[140:143], v[2:3], off offset:96
	v_readfirstlane_b32 s1, v0
	s_movk_i32 s0, 0xffc0
	s_cmp_eq_u32 s64, 1
	v_mov_b32_e32 v1, s1
	v_bfi_b32 v1, s0, v1, v0
	s_cselect_b64 s[12:13], -1, 0
	s_cmp_lg_u32 s64, 1
	v_ashrrev_i32_e32 v2, 4, v1
	v_lshrrev_b32_e32 v3, 4, v1
	v_lshlrev_b32_e32 v4, 11, v1
	v_add_u32_e32 v1, 0x200, v1
	s_cselect_b64 s[16:17], -1, 0
	s_lshl_b32 s0, s1, 4
	v_xor_b32_e32 v5, v2, v0
	v_lshlrev_b32_e32 v6, 11, v2
	v_xor_b32_e32 v2, v3, v0
	v_ashrrev_i32_e32 v3, 4, v1
	s_and_b32 s0, s0, 0xfffffc00
	v_lshlrev_b32_e32 v7, 4, v5
	v_lshlrev_b32_e32 v2, 3, v2
	v_xor_b32_e32 v5, v3, v0
	s_add_i32 s6, s0, 0
	v_lshlrev_b32_e32 v3, 11, v3
	v_and_b32_e32 v2, 56, v2
	v_lshlrev_b32_e32 v5, 4, v5
	v_and_or_b32 v162, v7, s3, v6
	s_mov_b32 m0, s6
	v_lshlrev_b32_e32 v1, 11, v1
	v_and_or_b32 v4, v4, s22, v2
	v_and_or_b32 v170, v5, s3, v3
	v_and_or_b32 v1, v1, s22, v2
	v_lshlrev_b32_e32 v166, 1, v4
	v_lshlrev_b32_e32 v168, 1, v1
	v_mov_b32_e32 v167, v163
	v_mov_b32_e32 v169, v163
	v_lshl_add_u64 v[2:3], s[20:21], 0, v[166:167]
	v_lshl_add_u64 v[4:5], s[20:21], 0, v[168:169]
	v_lshl_add_u64 v[2:3], v[2:3], 0, s[8:9]
	v_lshl_add_u64 v[4:5], v[4:5], 0, s[8:9]
	v_mov_b32_e32 v171, v163
	v_readlane_b32 s41, v255, 1
	v_readlane_b32 s42, v255, 2
	v_readlane_b32 s43, v255, 3
	v_readlane_b32 s44, v255, 4
	v_readlane_b32 s45, v255, 5
	v_readlane_b32 s46, v255, 6
	v_readlane_b32 s47, v255, 7
	v_readlane_b32 s48, v255, 8
	v_readlane_b32 s49, v255, 9
	v_readlane_b32 s50, v255, 10
	v_readlane_b32 s51, v255, 11
	v_readlane_b32 s54, v255, 14
	v_readlane_b32 s55, v255, 15
	s_waitcnt vmcnt(0)
	s_waitcnt vmcnt(0)
	global_load_lds_dwordx4 v162, s[14:15]
	s_add_i32 m0, s6, 0x2000
	s_nop 0
	global_load_lds_dwordx4 v170, s[14:15]
	s_add_i32 m0, s6, 0x4000
	s_nop 0
	global_load_lds_dwordx4 v166, s[20:21]
	s_add_i32 m0, s6, 0x6000
	s_nop 0
	global_load_lds_dwordx4 v168, s[20:21]
	s_add_i32 m0, s6, 0x8000
	s_add_u32 s0, s14, 0x20000
	s_addc_u32 s1, s15, 0
	global_load_lds_dwordx4 v162, s[0:1]
	s_add_i32 m0, s6, 0xa000
	s_and_b64 vcc, exec, s[12:13]
	global_load_lds_dwordx4 v170, s[0:1]
	s_add_i32 m0, s6, 0xc000
	s_mov_b64 s[0:1], -1
	global_load_lds_dwordx4 v[2:3], off
	s_add_i32 m0, s6, 0xe000
	s_nop 0
	global_load_lds_dwordx4 v[4:5], off
	s_min_u32 s65, s58, 2
	s_add_i32 m0, s6, 0x10000
	s_lshl_b32 s0, s65, 17
	s_add_u32 s0, s14, s0
	s_addc_u32 s1, s15, 0
	v_lshl_add_u64 v[2:3], s[0:1], 0, v[162:163]
	s_lshl_b32 s65, s65, 7
	global_load_lds_dwordx4 v[2:3], off
	s_add_i32 m0, s6, 0x12000
	v_lshl_add_u64 v[2:3], s[0:1], 0, v[170:171]
	s_add_u32 s0, s20, s65
	s_addc_u32 s1, s21, 0
	global_load_lds_dwordx4 v[2:3], off
	v_lshl_add_u64 v[2:3], s[0:1], 0, v[166:167]
	s_add_i32 m0, s6, 0x14000
	s_nop 0
	global_load_lds_dwordx4 v[2:3], off
	v_lshl_add_u64 v[2:3], s[0:1], 0, v[168:169]
	s_add_i32 m0, s6, 0x16000
	s_mov_b64 s[0:1], 0
	global_load_lds_dwordx4 v[2:3], off
	s_waitcnt vmcnt(8)

; DI void diff_core(unsigned char* smem, const u16* qptr, const u16* kbase, const u16* vtbase, int vld,
;                   int ntb, int ntw, int nvalid, int ks0, const float* lut, int qpos, bool active, bool grpB,
;                   f32x16 (&O)[4], float& l_out) {
;     ...
;     float mx = S[0][0];
; #pragma unroll
;     for (int kb = 0; kb < 2; ++kb)
; #pragma unroll
;       for (int i = 0; i < 16; ++i) mx = fmaxf(mx, S[kb][i]);
;     {
;       const unsigned um = __float_as_uint(mx);
;       const auto sw = __builtin_amdgcn_permlane32_swap(um, um, false, false);
;       mx = fmaxf(__uint_as_float(sw[0]), __uint_as_float(sw[1]));
;     }
;     if (t == 0) {
;       m = mx;
; #pragma unroll
;       for (int kb = 0; kb < 2; ++kb)
; #pragma unroll
;         for (int i = 0; i < 16; ++i) S[kb][i] -= mx;
;     } else if (__any(mx > 8.f)) {
;       const float d = fmaxf(mx, 0.f);
;       const float alpha = __builtin_amdgcn_exp2f(-d);
;       m += d;
;       l *= alpha;
; #pragma unroll
;       for (int tt = 0; tt < 4; ++tt)
; #pragma unroll
;         for (int e = 0; e < 16; ++e) O[tt][e] *= alpha;
; #pragma unroll
;       for (int kb = 0; kb < 2; ++kb)
; #pragma unroll
;         for (int i = 0; i < 16; ++i) S[kb][i] -= d;
;     }
;     float ps = 0.f;
; #pragma unroll
;     for (int kb = 0; kb < 2; ++kb)
; #pragma unroll
;       for (int i = 0; i < 16; ++i) {
;         const float pe = __builtin_amdgcn_exp2f(S[kb][i]);
;         S[kb][i] = pe;
;         ps += pe;
;       }
;     l += ps;
.LBB0_357:
	v_max_f32_e32 v32, v1, v1
	v_max_f32_e32 v33, v0, v0
	v_max_f32_e32 v32, v33, v32
	v_max3_f32 v32, v32, v2, v3
	v_max3_f32 v32, v32, v4, v5
	v_max3_f32 v32, v32, v6, v7
	v_max3_f32 v32, v32, v8, v9
	v_max3_f32 v32, v32, v10, v11
	v_max3_f32 v32, v32, v12, v13
	v_max3_f32 v32, v32, v14, v15
	v_max3_f32 v32, v32, v16, v17
	v_max3_f32 v32, v32, v18, v19
	v_max3_f32 v32, v32, v20, v21
	v_max3_f32 v32, v32, v22, v23
	v_max3_f32 v32, v32, v24, v25
	v_max3_f32 v32, v32, v26, v27
	v_max3_f32 v32, v32, v28, v29
	v_max3_f32 v32, v32, v30, v31
	v_mov_b32_e32 v33, v32
	s_nop 1
	v_permlane32_swap_b32_e32 v32, v33
	v_max_f32_e32 v33, v33, v33
	v_max_f32_e32 v32, v32, v32
	v_max_f32_e32 v191, v32, v33
	v_xor_b32_e32 v232, 0x80000000, v191
	v_mov_b32_e32 v233, v232
	v_mov_b32_e32 v234, v232
	v_mov_b32_e32 v235, v232
	v_mov_b32_e32 v236, v232
	v_mov_b32_e32 v237, v232
	v_mov_b32_e32 v238, v232
	v_mov_b32_e32 v239, v232
	v_mov_b32_e32 v240, v232
	v_mov_b32_e32 v241, v232
	v_mov_b32_e32 v242, v232
	v_mov_b32_e32 v243, v232
	v_mov_b32_e32 v244, v232
	v_mov_b32_e32 v245, v232
	v_mov_b32_e32 v246, v232
	v_mov_b32_e32 v247, v232
	v_sub_f32_e32 v0, v0, v191
	v_sub_f32_e32 v1, v1, v191
	v_exp_f32_e32 v96, v0
	v_sub_f32_e32 v2, v2, v191
	v_exp_f32_e32 v97, v1
	v_sub_f32_e32 v3, v3, v191
	v_exp_f32_e32 v98, v2
	v_sub_f32_e32 v4, v4, v191
	v_exp_f32_e32 v99, v3
	v_sub_f32_e32 v5, v5, v191
	v_exp_f32_e32 v100, v4
	v_sub_f32_e32 v6, v6, v191
	v_exp_f32_e32 v101, v5
	v_sub_f32_e32 v7, v7, v191
	v_exp_f32_e32 v102, v6
	v_sub_f32_e32 v8, v8, v191
	v_exp_f32_e32 v103, v7
	v_sub_f32_e32 v9, v9, v191
	v_exp_f32_e32 v104, v8
	v_sub_f32_e32 v10, v10, v191
	v_exp_f32_e32 v105, v9
	v_sub_f32_e32 v11, v11, v191
	v_exp_f32_e32 v106, v10
	v_sub_f32_e32 v12, v12, v191
	v_exp_f32_e32 v107, v11
	v_sub_f32_e32 v13, v13, v191
	v_exp_f32_e32 v108, v12
	v_sub_f32_e32 v14, v14, v191
	v_exp_f32_e32 v109, v13
	v_sub_f32_e32 v15, v15, v191
	v_exp_f32_e32 v110, v14
	v_sub_f32_e32 v16, v16, v191
	v_exp_f32_e32 v111, v15
	v_sub_f32_e32 v17, v17, v191
	v_exp_f32_e32 v112, v16
	v_sub_f32_e32 v18, v18, v191
	v_exp_f32_e32 v113, v17
	v_sub_f32_e32 v19, v19, v191
	v_exp_f32_e32 v114, v18
	v_sub_f32_e32 v20, v20, v191
	v_exp_f32_e32 v115, v19
	v_sub_f32_e32 v21, v21, v191
	v_exp_f32_e32 v116, v20
	v_sub_f32_e32 v22, v22, v191
	v_exp_f32_e32 v117, v21
	v_sub_f32_e32 v23, v23, v191
	v_exp_f32_e32 v118, v22
	v_sub_f32_e32 v24, v24, v191
	v_exp_f32_e32 v119, v23
	v_sub_f32_e32 v25, v25, v191
	v_exp_f32_e32 v120, v24
	v_sub_f32_e32 v26, v26, v191
	v_exp_f32_e32 v121, v25
	v_sub_f32_e32 v27, v27, v191
	v_exp_f32_e32 v122, v26
	v_sub_f32_e32 v28, v28, v191
	v_exp_f32_e32 v123, v27
	v_sub_f32_e32 v29, v29, v191
	v_exp_f32_e32 v124, v28
	v_sub_f32_e32 v30, v30, v191
	v_exp_f32_e32 v125, v29
	v_sub_f32_e32 v31, v31, v191
	v_exp_f32_e32 v126, v30
	v_exp_f32_e32 v127, v31
	s_lshl_b32 s0, s62, 1
	s_sub_i32 s63, 0, s0
	s_lshl_b32 s0, s59, 10
	s_lshl_b32 s1, s62, 9
	s_add_i32 s0, s0, s1
	v_mov_b32_e32 v181, 0
	v_or_b32_e32 v0, s0, v183
	v_lshlrev_b32_e32 v1, 2, v182
	v_sub_u32_e32 v0, v0, v1
	s_lshl_b32 s0, s39, 7
	v_subrev_u32_e32 v0, s0, v0
	v_mov_b32_e32 v14, v163
	v_mov_b32_e32 v15, v163
	v_add_u32_e32 v199, s38, v0
	v_mov_b32_e32 v0, v163
	v_mov_b32_e32 v1, v163
	v_mov_b32_e32 v2, v163
	v_mov_b32_e32 v3, v163
	v_mov_b32_e32 v4, v163
	v_mov_b32_e32 v5, v163
	v_mov_b32_e32 v6, v163
	v_mov_b32_e32 v7, v163
	v_mov_b32_e32 v8, v163
	v_mov_b32_e32 v9, v163
	v_mov_b32_e32 v10, v163
	v_mov_b32_e32 v11, v163
	v_mov_b32_e32 v12, v163
	v_mov_b32_e32 v13, v163
	v_mov_b64_e32 v[30:31], v[14:15]
	v_mov_b64_e32 v[46:47], v[14:15]
	v_mov_b64_e32 v[62:63], v[14:15]
	v_add_u32_e32 v195, v188, v184
	v_add_u32_e32 v196, v187, v184
	v_add_u32_e32 v197, v186, v184
	v_add_u32_e32 v198, v185, v184
	s_movk_i32 s64, 0xff00
	s_mov_b32 s65, 0x20000
	v_mov_b64_e32 v[28:29], v[12:13]
	v_mov_b64_e32 v[26:27], v[10:11]
	v_mov_b64_e32 v[24:25], v[8:9]
	v_mov_b64_e32 v[22:23], v[6:7]
	v_mov_b64_e32 v[20:21], v[4:5]
	v_mov_b64_e32 v[18:19], v[2:3]
	v_mov_b64_e32 v[16:17], v[0:1]
	v_mov_b64_e32 v[44:45], v[12:13]
	v_mov_b64_e32 v[42:43], v[10:11]
	v_mov_b64_e32 v[40:41], v[8:9]
	v_mov_b64_e32 v[38:39], v[6:7]
	v_mov_b64_e32 v[36:37], v[4:5]
	v_mov_b64_e32 v[34:35], v[2:3]
	v_mov_b64_e32 v[32:33], v[0:1]
	v_mov_b64_e32 v[60:61], v[12:13]
	v_mov_b64_e32 v[58:59], v[10:11]
	v_mov_b64_e32 v[56:57], v[8:9]
	v_mov_b64_e32 v[54:55], v[6:7]
	v_mov_b64_e32 v[52:53], v[4:5]
	v_mov_b64_e32 v[50:51], v[2:3]
	v_mov_b64_e32 v[48:49], v[0:1]
	s_branch .LBB0_360
.LBB0_358:
	v_exp_f32_e32 v96, v96
	v_exp_f32_e32 v97, v97
	v_exp_f32_e32 v98, v98
	v_exp_f32_e32 v99, v99
	v_exp_f32_e32 v100, v100
	v_exp_f32_e32 v101, v101
	v_exp_f32_e32 v102, v102
	v_exp_f32_e32 v103, v103
	v_exp_f32_e32 v104, v104
	v_exp_f32_e32 v105, v105
	v_exp_f32_e32 v106, v106
	v_exp_f32_e32 v107, v107
	v_exp_f32_e32 v108, v108
	v_exp_f32_e32 v109, v109
	v_exp_f32_e32 v110, v110
	v_exp_f32_e32 v111, v111
	v_exp_f32_e32 v112, v112
	v_exp_f32_e32 v113, v113
	v_exp_f32_e32 v114, v114
	v_exp_f32_e32 v115, v115
	v_exp_f32_e32 v116, v116
	v_exp_f32_e32 v117, v117
	v_exp_f32_e32 v118, v118
	v_exp_f32_e32 v119, v119
	v_exp_f32_e32 v120, v120
	v_exp_f32_e32 v121, v121
	v_exp_f32_e32 v122, v122
	v_exp_f32_e32 v123, v123
	v_exp_f32_e32 v124, v124
	v_exp_f32_e32 v125, v125
	v_exp_f32_e32 v126, v126
	v_exp_f32_e32 v127, v127

; #define LAS __attribute__((address_space(3)))
; DI void diff_core(unsigned char* smem, const u16* qptr, const u16* kbase, const u16* vtbase, int vld,
;                   int ntb, int ntw, int nvalid, int ks0, const float* lut, int qpos, bool active, bool grpB,
;                   f32x16 (&O)[4], float& l_out) {
;     ...
;     for (int s = 0; s < 4; ++s)
; #pragma unroll
;       for (int kb = 0; kb < 2; ++kb) kf[s][kb] = *reinterpret_cast<const LAS bf16x8*>(b + koff[s] + kb * 32 * 256);
; #pragma unroll
;     for (int s = 0; s < 4; ++s)
; #pragma unroll
;       for (int kb = 0; kb < 2; ++kb) S[kb] = MFMA(kf[s][kb], qf[s], S[kb]);
;     ...
;   auto pv = [&](int slot) {
;     if (grpB) __builtin_amdgcn_s_setprio(2); else __builtin_amdgcn_s_setprio(1);
;     const LAS unsigned char* b = lds + slot * D_SLOT;
;     bf16x8 va[4], vb[4];
; #pragma unroll
;     for (int tt = 0; tt < 4; ++tt) va[tt] = *reinterpret_cast<const LAS bf16x8*>(b + voff[0] + tt * 32 * 128);
; #pragma unroll
;     for (int tt = 0; tt < 4; ++tt) vb[tt] = *reinterpret_cast<const LAS bf16x8*>(b + voff[1] + tt * 32 * 128);
;     {
;       const bf16x8 pf = __builtin_bit_cast(bf16x8, P[0]);
; #pragma unroll
;       for (int tt = 0; tt < 4; ++tt) O[tt] = MFMA(va[tt], pf, O[tt]);
;     }
; #pragma unroll
;     for (int tt = 0; tt < 4; ++tt) va[tt] = *reinterpret_cast<const LAS bf16x8*>(b + voff[2] + tt * 32 * 128);
;     {
;       const bf16x8 pf = __builtin_bit_cast(bf16x8, P[1]);
; #pragma unroll
;       for (int tt = 0; tt < 4; ++tt) O[tt] = MFMA(vb[tt], pf, O[tt]);
;     }
; #pragma unroll
;     for (int tt = 0; tt < 4; ++tt) vb[tt] = *reinterpret_cast<const LAS bf16x8*>(b + voff[3] + tt * 32 * 128);
;     {
;       const bf16x8 pf = __builtin_bit_cast(bf16x8, P[2]);
; #pragma unroll
;       for (int tt = 0; tt < 4; ++tt) O[tt] = MFMA(va[tt], pf, O[tt]);
;     }
;     {
;       const bf16x8 pf = __builtin_bit_cast(bf16x8, P[3]);
; #pragma unroll
;       for (int tt = 0; tt < 4; ++tt) O[tt] = MFMA(vb[tt], pf, O[tt]);
;     }
;     __builtin_amdgcn_sched_group_barrier(0x100, 8, 0);
;     __builtin_amdgcn_sched_group_barrier(0x008, 4, 0);
;     __builtin_amdgcn_sched_group_barrier(0x100, 4, 0);
;     __builtin_amdgcn_sched_group_barrier(0x008, 4, 0);
;     __builtin_amdgcn_sched_group_barrier(0x100, 4, 0);
;     __builtin_amdgcn_sched_group_barrier(0x008, 8, 0);
;     __builtin_amdgcn_s_setprio(0);
;   };
.LBB0_360:
	s_add_i32 s66, s64, 0x101
	s_cmp_gt_u32 s66, s16
	s_cbranch_scc1 .LBB0_362
	s_setprio 1
	s_and_b32 s0, s65, 0x18000
	v_add_u32_e32 v212, s0, v195
	ds_read_b128 v[200:203], v212 offset:16384
	ds_read_b128 v[204:207], v212 offset:20480
	ds_read_b128 v[208:211], v212 offset:24576
	ds_read_b128 v[212:215], v212 offset:28672
	v_add_u32_e32 v228, s0, v196
	ds_read_b128 v[216:219], v228 offset:16384
	ds_read_b128 v[220:223], v228 offset:20480
	ds_read_b128 v[224:227], v228 offset:24576
	ds_read_b128 v[228:231], v228 offset:28672
	s_add_i32 s67, s65, 0xfffe8000
	s_and_b32 s67, s67, 0x18000
	v_cvt_pk_bf16_f32 v144, v96, v97
	v_cvt_pk_bf16_f32 v145, v98, v99
	v_cvt_pk_bf16_f32 v146, v100, v101
	v_cvt_pk_bf16_f32 v147, v102, v103
	v_add_f32_e32 v250, v97, v96
	v_add_f32_e32 v250, v98, v250
	s_waitcnt lgkmcnt(0)
	v_mfma_f32_32x32x16_bf16 v[48:63], v[200:203], v[144:147], v[48:63]
	v_cvt_pk_bf16_f32 v148, v104, v105
	v_add_f32_e32 v250, v99, v250
	v_add_f32_e32 v250, v100, v250
	v_mfma_f32_32x32x16_bf16 v[32:47], v[204:207], v[144:147], v[32:47]
	v_cvt_pk_bf16_f32 v149, v106, v107
	v_add_f32_e32 v250, v101, v250
	v_add_f32_e32 v250, v102, v250
	v_mfma_f32_32x32x16_bf16 v[16:31], v[208:211], v[144:147], v[16:31]
	v_cvt_pk_bf16_f32 v150, v108, v109
	v_add_f32_e32 v250, v103, v250
	v_add_f32_e32 v250, v104, v250
	v_mfma_f32_32x32x16_bf16 v[0:15], v[212:215], v[144:147], v[0:15]
	v_cvt_pk_bf16_f32 v151, v110, v111
	v_add_f32_e32 v250, v105, v250
	v_add_f32_e32 v250, v106, v250
	v_add_u32_e32 v212, s0, v197
	ds_read_b128 v[200:203], v212 offset:16384
	ds_read_b128 v[204:207], v212 offset:20480
	ds_read_b128 v[208:211], v212 offset:24576
	ds_read_b128 v[212:215], v212 offset:28672
	v_mfma_f32_32x32x16_bf16 v[48:63], v[216:219], v[148:151], v[48:63]
	v_cvt_pk_bf16_f32 v152, v112, v113
	v_add_f32_e32 v250, v107, v250
	v_add_f32_e32 v250, v108, v250
	v_mfma_f32_32x32x16_bf16 v[32:47], v[220:223], v[148:151], v[32:47]
	v_cvt_pk_bf16_f32 v153, v114, v115
	v_add_f32_e32 v250, v109, v250
	v_add_f32_e32 v250, v110, v250
	v_mfma_f32_32x32x16_bf16 v[16:31], v[224:227], v[148:151], v[16:31]
	v_cvt_pk_bf16_f32 v154, v116, v117
	v_add_f32_e32 v250, v111, v250
	v_add_f32_e32 v250, v112, v250
	v_mfma_f32_32x32x16_bf16 v[0:15], v[228:231], v[148:151], v[0:15]
	v_cvt_pk_bf16_f32 v155, v118, v119
	v_add_f32_e32 v250, v113, v250
	v_add_f32_e32 v250, v114, v250
	v_add_u32_e32 v228, s0, v198
	ds_read_b128 v[216:219], v228 offset:16384
	ds_read_b128 v[220:223], v228 offset:20480
	ds_read_b128 v[224:227], v228 offset:24576
	ds_read_b128 v[228:231], v228 offset:28672
	v_add_u32_e32 v248, s67, v177
	ds_read_b128 v[64:67], v248
	ds_read_b128 v[68:71], v248 offset:8192
	v_add_u32_e32 v249, s67, v178
	ds_read_b128 v[72:75], v249
	ds_read_b128 v[76:79], v249 offset:8192
	s_waitcnt lgkmcnt(8)
	v_mfma_f32_32x32x16_bf16 v[48:63], v[200:203], v[152:155], v[48:63]
	v_cvt_pk_bf16_f32 v156, v120, v121
	v_add_f32_e32 v250, v115, v250
	v_add_f32_e32 v250, v116, v250
	v_mfma_f32_32x32x16_bf16 v[32:47], v[204:207], v[152:155], v[32:47]
	v_cvt_pk_bf16_f32 v157, v122, v123
	v_add_f32_e32 v250, v117, v250
	v_add_f32_e32 v250, v118, v250
	v_mfma_f32_32x32x16_bf16 v[16:31], v[208:211], v[152:155], v[16:31]
	v_cvt_pk_bf16_f32 v158, v124, v125
	v_add_f32_e32 v250, v119, v250
	v_add_f32_e32 v250, v120, v250
	v_mfma_f32_32x32x16_bf16 v[0:15], v[212:215], v[152:155], v[0:15]
	v_cvt_pk_bf16_f32 v159, v126, v127
	v_add_f32_e32 v250, v121, v250
	v_add_f32_e32 v250, v122, v250
	v_add_u32_e32 v248, s67, v179
	ds_read_b128 v[80:83], v248
	ds_read_b128 v[84:87], v248 offset:8192
	v_add_u32_e32 v249, s67, v180
	ds_read_b128 v[88:91], v249
	ds_read_b128 v[92:95], v249 offset:8192
	s_waitcnt lgkmcnt(8)
	v_mfma_f32_32x32x16_bf16 v[48:63], v[216:219], v[156:159], v[48:63]
	v_add_f32_e32 v250, v123, v250
	v_add_f32_e32 v250, v124, v250
	v_mfma_f32_32x32x16_bf16 v[32:47], v[220:223], v[156:159], v[32:47]
	v_add_f32_e32 v250, v125, v250
	v_add_f32_e32 v250, v126, v250
	v_mfma_f32_32x32x16_bf16 v[16:31], v[224:227], v[156:159], v[16:31]
	v_add_f32_e32 v250, v127, v250
	v_mfma_f32_32x32x16_bf16 v[0:15], v[228:231], v[156:159], v[0:15]
	v_add_f32_e32 v181, v181, v250
	s_setprio 0
.LBB0_362:
	s_cmp_lt_u32 s66, s16
	s_cselect_b64 s[0:1], -1, 0
	s_cmp_ge_u32 s66, s16
	s_cbranch_scc1 .LBB0_364
	s_setprio 1
	s_waitcnt lgkmcnt(0)
	v_mfma_f32_32x32x16_bf16 v[96:111], v[64:67], v[128:131], v[232:247]
	v_mfma_f32_32x32x16_bf16 v[112:127], v[68:71], v[128:131], v[232:247]
	v_mfma_f32_32x32x16_bf16 v[96:111], v[72:75], v[132:135], v[96:111]
	v_mfma_f32_32x32x16_bf16 v[112:127], v[76:79], v[132:135], v[112:127]
	v_mfma_f32_32x32x16_bf16 v[96:111], v[80:83], v[136:139], v[96:111]
	v_mfma_f32_32x32x16_bf16 v[112:127], v[84:87], v[136:139], v[112:127]
	v_mfma_f32_32x32x16_bf16 v[96:111], v[88:91], v[140:143], v[96:111]
	v_mfma_f32_32x32x16_bf16 v[112:127], v[92:95], v[140:143], v[112:127]
	s_setprio 0
; DI int crow(int i, int hh) { return (i & 3) + 8 * (i >> 2) + 4 * hh; }
; #define D_BAR do { asm volatile("" ::: "memory"); __builtin_amdgcn_s_barrier(); asm volatile("" ::: "memory"); } while (0)
; DI void diff_core(unsigned char* smem, const u16* qptr, const u16* kbase, const u16* vtbase, int vld,
;                   int ntb, int ntw, int nvalid, int ks0, const float* lut, int qpos, bool active, bool grpB,
;                   f32x16 (&O)[4], float& l_out) {
;     ...
;     if (lut != nullptr && t >= ntw - 3) {
;       const int base = t * 64 - qpos + 191;
; #pragma unroll
;       for (int kb = 0; kb < 2; ++kb)
; #pragma unroll
;         for (int i = 0; i < 16; ++i) S[kb][i] += lut[base + kb * 32 + crow(i, hh)];
;     }
;     ...
;       asm volatile("s_waitcnt vmcnt(4)" ::: "memory");
;       D_BAR;
;       { const int tn = t + 3; dma(tn < tlast ? tn : tlast, tn & 3); }
;       if (act_t) softmax(t);
.LBB0_364:
	s_add_i32 s67, s64, 0x104
	s_min_i32 s67, s67, s58
	s_lshl_b32 s86, s67, 6
	s_and_b32 s85, s65, 0x18000
	s_ashr_i32 s87, s86, 31
	s_add_i32 s85, s6, s85
	s_lshl_b64 s[88:89], s[86:87], 11
	s_add_u32 s88, s14, s88
	s_waitcnt vmcnt(4)
	s_addc_u32 s89, s15, s89
	s_barrier
	s_mov_b32 m0, s85
	s_lshl_b64 s[86:87], s[86:87], 1
	global_load_lds_dwordx4 v162, s[88:89]
	s_add_i32 m0, s85, 0x2000
	s_add_u32 s86, s20, s86
	s_addc_u32 s87, s21, s87
	global_load_lds_dwordx4 v170, s[88:89]
	s_add_i32 m0, s85, 0x4000
	s_andn2_b64 vcc, exec, s[0:1]
	global_load_lds_dwordx4 v166, s[86:87]
	s_add_i32 m0, s85, 0x6000
	s_nop 0
	global_load_lds_dwordx4 v168, s[86:87]
	s_cbranch_vccnz .LBB0_359
	s_cmp_lt_i32 s66, s17
	s_cbranch_scc1 .LBB0_367
	ds_read2_b32 v[144:145], v199 offset1:1
	ds_read2_b32 v[146:147], v199 offset0:16 offset1:17
	ds_read2_b32 v[148:149], v199 offset0:18 offset1:19
	ds_read2_b32 v[150:151], v199 offset0:24 offset1:25
	ds_read2_b32 v[152:153], v199 offset0:26 offset1:27
	ds_read2_b32 v[154:155], v199 offset0:2 offset1:3
	ds_read2_b32 v[156:157], v199 offset0:8 offset1:9
	ds_read2_b32 v[158:159], v199 offset0:10 offset1:11
	s_waitcnt lgkmcnt(0)
	v_pk_add_f32 v[96:97], v[96:97], v[144:145]
	v_pk_add_f32 v[110:111], v[110:111], v[152:153]
	v_pk_add_f32 v[108:109], v[108:109], v[150:151]
	v_pk_add_f32 v[106:107], v[106:107], v[148:149]
	v_pk_add_f32 v[104:105], v[104:105], v[146:147]
	v_pk_add_f32 v[102:103], v[102:103], v[158:159]
	v_pk_add_f32 v[100:101], v[100:101], v[156:157]
	v_pk_add_f32 v[98:99], v[98:99], v[154:155]
	ds_read2_b32 v[144:145], v199 offset0:32 offset1:33
	ds_read2_b32 v[146:147], v199 offset0:48 offset1:49
	ds_read2_b32 v[148:149], v199 offset0:50 offset1:51
	ds_read2_b32 v[150:151], v199 offset0:56 offset1:57
	ds_read2_b32 v[152:153], v199 offset0:58 offset1:59
	ds_read2_b32 v[154:155], v199 offset0:34 offset1:35
	ds_read2_b32 v[156:157], v199 offset0:40 offset1:41
	ds_read2_b32 v[158:159], v199 offset0:42 offset1:43
	s_waitcnt lgkmcnt(0)
	v_pk_add_f32 v[112:113], v[112:113], v[144:145]
	v_pk_add_f32 v[126:127], v[126:127], v[152:153]
	v_pk_add_f32 v[124:125], v[124:125], v[150:151]
	v_pk_add_f32 v[122:123], v[122:123], v[148:149]
	v_pk_add_f32 v[120:121], v[120:121], v[146:147]
	v_pk_add_f32 v[118:119], v[118:119], v[158:159]
	v_pk_add_f32 v[116:117], v[116:117], v[156:157]
	v_pk_add_f32 v[114:115], v[114:115], v[154:155]
; DI void diff_core(unsigned char* smem, const u16* qptr, const u16* kbase, const u16* vtbase, int vld,
;                   int ntb, int ntw, int nvalid, int ks0, const float* lut, int qpos, bool active, bool grpB,
;                   f32x16 (&O)[4], float& l_out) {
;     ...
;     float mx = S[0][0];
; #pragma unroll
;     for (int kb = 0; kb < 2; ++kb)
; #pragma unroll
;       for (int i = 0; i < 16; ++i) mx = fmaxf(mx, S[kb][i]);
;     {
;       const unsigned um = __float_as_uint(mx);
;       const auto sw = __builtin_amdgcn_permlane32_swap(um, um, false, false);
;       mx = fmaxf(__uint_as_float(sw[0]), __uint_as_float(sw[1]));
;     }
;     if (t == 0) {
;       m = mx;
; #pragma unroll
;       for (int kb = 0; kb < 2; ++kb)
; #pragma unroll
;         for (int i = 0; i < 16; ++i) S[kb][i] -= mx;
;     } else if (__any(mx > 8.f)) {
;       const float d = fmaxf(mx, 0.f);
;       const float alpha = __builtin_amdgcn_exp2f(-d);
;       m += d;
;       l *= alpha;
; #pragma unroll
;       for (int tt = 0; tt < 4; ++tt)
; #pragma unroll
;         for (int e = 0; e < 16; ++e) O[tt][e] *= alpha;
; #pragma unroll
;       for (int kb = 0; kb < 2; ++kb)
; #pragma unroll
;         for (int i = 0; i < 16; ++i) S[kb][i] -= d;
;     }
.LBB0_367:
	v_max_f32_e32 v144, v97, v97
	v_max_f32_e32 v145, v96, v96
	v_max_f32_e32 v144, v145, v144
	v_max3_f32 v144, v144, v98, v99
	v_max3_f32 v144, v144, v100, v101
	v_max3_f32 v144, v144, v102, v103
	v_max3_f32 v144, v144, v104, v105
	v_max3_f32 v144, v144, v106, v107
	v_max3_f32 v144, v144, v108, v109
	v_max3_f32 v144, v144, v110, v111
	v_max3_f32 v144, v144, v112, v113
	v_max3_f32 v144, v144, v114, v115
	v_max3_f32 v144, v144, v116, v117
	v_max3_f32 v144, v144, v118, v119
	v_max3_f32 v144, v144, v120, v121
	v_max3_f32 v144, v144, v122, v123
	v_max3_f32 v144, v144, v124, v125
	v_max3_f32 v144, v144, v126, v127
	v_mov_b32_e32 v145, v144
	s_nop 1
	v_permlane32_swap_b32_e32 v144, v145
	v_max_f32_e32 v144, v144, v145
	v_cmp_lt_f32_e32 vcc, s23, v144
	s_cbranch_vccz .LBB0_358
	v_max_f32_e32 v144, v144, v144
	v_max_f32_e32 v144, 0, v144
	v_exp_f32_e64 v146, -v144
	v_add_f32_e32 v191, v191, v144
	v_xor_b32_e32 v232, 0x80000000, v191
	v_mov_b32_e32 v233, v232
	v_mov_b32_e32 v234, v232
	v_mov_b32_e32 v235, v232
	v_mov_b32_e32 v236, v232
	v_mov_b32_e32 v237, v232
	v_mov_b32_e32 v238, v232
	v_mov_b32_e32 v239, v232
	v_mov_b32_e32 v240, v232
	v_mov_b32_e32 v241, v232
	v_mov_b32_e32 v242, v232
	v_mov_b32_e32 v243, v232
	v_mov_b32_e32 v244, v232
	v_mov_b32_e32 v245, v232
	v_mov_b32_e32 v246, v232
	v_mov_b32_e32 v247, v232
	v_pk_add_f32 v[96:97], v[96:97], v[144:145] op_sel_hi:[1,0] neg_lo:[0,1] neg_hi:[0,1]
	v_pk_add_f32 v[98:99], v[98:99], v[144:145] op_sel_hi:[1,0] neg_lo:[0,1] neg_hi:[0,1]
	v_pk_mul_f32 v[14:15], v[14:15], v[146:147] op_sel_hi:[1,0]
	v_pk_mul_f32 v[12:13], v[12:13], v[146:147] op_sel_hi:[1,0]
	v_pk_mul_f32 v[10:11], v[10:11], v[146:147] op_sel_hi:[1,0]
	v_pk_mul_f32 v[8:9], v[8:9], v[146:147] op_sel_hi:[1,0]
	v_pk_mul_f32 v[6:7], v[6:7], v[146:147] op_sel_hi:[1,0]
	v_pk_mul_f32 v[4:5], v[4:5], v[146:147] op_sel_hi:[1,0]
	v_pk_mul_f32 v[2:3], v[2:3], v[146:147] op_sel_hi:[1,0]
	v_pk_mul_f32 v[0:1], v[0:1], v[146:147] op_sel_hi:[1,0]
	v_pk_mul_f32 v[30:31], v[30:31], v[146:147] op_sel_hi:[1,0]
	v_pk_mul_f32 v[28:29], v[28:29], v[146:147] op_sel_hi:[1,0]
	v_pk_mul_f32 v[26:27], v[26:27], v[146:147] op_sel_hi:[1,0]
	v_pk_mul_f32 v[24:25], v[24:25], v[146:147] op_sel_hi:[1,0]
	v_pk_mul_f32 v[22:23], v[22:23], v[146:147] op_sel_hi:[1,0]
	v_pk_mul_f32 v[20:21], v[20:21], v[146:147] op_sel_hi:[1,0]
	v_pk_mul_f32 v[18:19], v[18:19], v[146:147] op_sel_hi:[1,0]
	v_pk_mul_f32 v[16:17], v[16:17], v[146:147] op_sel_hi:[1,0]
	v_pk_mul_f32 v[46:47], v[46:47], v[146:147] op_sel_hi:[1,0]
	v_pk_mul_f32 v[44:45], v[44:45], v[146:147] op_sel_hi:[1,0]
	v_pk_mul_f32 v[42:43], v[42:43], v[146:147] op_sel_hi:[1,0]
	v_pk_mul_f32 v[40:41], v[40:41], v[146:147] op_sel_hi:[1,0]
	v_pk_mul_f32 v[38:39], v[38:39], v[146:147] op_sel_hi:[1,0]
	v_pk_mul_f32 v[36:37], v[36:37], v[146:147] op_sel_hi:[1,0]
	v_pk_mul_f32 v[34:35], v[34:35], v[146:147] op_sel_hi:[1,0]
	v_pk_mul_f32 v[32:33], v[32:33], v[146:147] op_sel_hi:[1,0]
	v_pk_mul_f32 v[62:63], v[62:63], v[146:147] op_sel_hi:[1,0]
	v_pk_mul_f32 v[60:61], v[60:61], v[146:147] op_sel_hi:[1,0]
	v_pk_mul_f32 v[58:59], v[58:59], v[146:147] op_sel_hi:[1,0]
	v_pk_mul_f32 v[56:57], v[56:57], v[146:147] op_sel_hi:[1,0]
	v_pk_mul_f32 v[54:55], v[54:55], v[146:147] op_sel_hi:[1,0]
	v_pk_mul_f32 v[52:53], v[52:53], v[146:147] op_sel_hi:[1,0]
	v_pk_mul_f32 v[50:51], v[50:51], v[146:147] op_sel_hi:[1,0]
	v_pk_mul_f32 v[48:49], v[48:49], v[146:147] op_sel_hi:[1,0]
	v_mul_f32_e32 v181, v181, v146
	v_pk_add_f32 v[100:101], v[100:101], v[144:145] op_sel_hi:[1,0] neg_lo:[0,1] neg_hi:[0,1]
	v_pk_add_f32 v[102:103], v[102:103], v[144:145] op_sel_hi:[1,0] neg_lo:[0,1] neg_hi:[0,1]
	v_pk_add_f32 v[104:105], v[104:105], v[144:145] op_sel_hi:[1,0] neg_lo:[0,1] neg_hi:[0,1]
	v_pk_add_f32 v[106:107], v[106:107], v[144:145] op_sel_hi:[1,0] neg_lo:[0,1] neg_hi:[0,1]
	v_pk_add_f32 v[108:109], v[108:109], v[144:145] op_sel_hi:[1,0] neg_lo:[0,1] neg_hi:[0,1]
	v_pk_add_f32 v[110:111], v[110:111], v[144:145] op_sel_hi:[1,0] neg_lo:[0,1] neg_hi:[0,1]
	v_pk_add_f32 v[112:113], v[112:113], v[144:145] op_sel_hi:[1,0] neg_lo:[0,1] neg_hi:[0,1]
	v_pk_add_f32 v[114:115], v[114:115], v[144:145] op_sel_hi:[1,0] neg_lo:[0,1] neg_hi:[0,1]
	v_pk_add_f32 v[116:117], v[116:117], v[144:145] op_sel_hi:[1,0] neg_lo:[0,1] neg_hi:[0,1]
	v_pk_add_f32 v[118:119], v[118:119], v[144:145] op_sel_hi:[1,0] neg_lo:[0,1] neg_hi:[0,1]
	v_pk_add_f32 v[120:121], v[120:121], v[144:145] op_sel_hi:[1,0] neg_lo:[0,1] neg_hi:[0,1]
	v_pk_add_f32 v[122:123], v[122:123], v[144:145] op_sel_hi:[1,0] neg_lo:[0,1] neg_hi:[0,1]
	v_pk_add_f32 v[124:125], v[124:125], v[144:145] op_sel_hi:[1,0] neg_lo:[0,1] neg_hi:[0,1]
	v_pk_add_f32 v[126:127], v[126:127], v[144:145] op_sel_hi:[1,0] neg_lo:[0,1] neg_hi:[0,1]
	s_branch .LBB0_358

; DI int crow(int i, int hh) { return (i & 3) + 8 * (i >> 2) + 4 * hh; }
; DI void diff_core(unsigned char* smem, const u16* qptr, const u16* kbase, const u16* vtbase, int vld,
;                   int ntb, int ntw, int nvalid, int ks0, const float* lut, int qpos, bool active, bool grpB,
;                   f32x16 (&O)[4], float& l_out) {
;     ...
;     if (lut != nullptr && t >= ntw - 3) {
;       const int base = t * 64 - qpos + 191;
; #pragma unroll
;       for (int kb = 0; kb < 2; ++kb)
; #pragma unroll
;         for (int i = 0; i < 16; ++i) S[kb][i] += lut[base + kb * 32 + crow(i, hh)];
;     }
;     if (t == ntw - 1 && nvalid < 64) {
; #pragma unroll
;       for (int kb = 0; kb < 2; ++kb)
; #pragma unroll
;         for (int i = 0; i < 16; ++i)
;           if (kb * 32 + crow(i, hh) >= nvalid) S[kb][i] = -1e30f;
;     }
;     float mx = S[0][0];
; #pragma unroll
;     for (int kb = 0; kb < 2; ++kb)
; #pragma unroll
;       for (int i = 0; i < 16; ++i) mx = fmaxf(mx, S[kb][i]);
;     {
;       const unsigned um = __float_as_uint(mx);
;       const auto sw = __builtin_amdgcn_permlane32_swap(um, um, false, false);
;       mx = fmaxf(__uint_as_float(sw[0]), __uint_as_float(sw[1]));
;     }
;     if (t == 0) {
;       m = mx;
; #pragma unroll
;       for (int kb = 0; kb < 2; ++kb)
; #pragma unroll
;         for (int i = 0; i < 16; ++i) S[kb][i] -= mx;
.LBB0_370:
	s_and_b64 vcc, exec, s[0:1]
	s_cbranch_vccz .LBB0_388
	s_cmp_gt_u32 s16, 3
	s_cbranch_scc1 .LBB0_373
	v_lshlrev_b32_e32 v0, 2, v189
	v_sub_u32_e32 v16, v190, v0
	ds_read2_b32 v[0:1], v16 offset0:207 offset1:208
	ds_read2_b32 v[2:3], v16 offset0:209 offset1:210
	ds_read2_b32 v[4:5], v16 offset0:215 offset1:216
	ds_read2_b32 v[6:7], v16 offset0:217 offset1:218
	ds_read2_b32 v[8:9], v16 offset0:191 offset1:192
	ds_read2_b32 v[10:11], v16 offset0:193 offset1:194
	ds_read2_b32 v[12:13], v16 offset0:199 offset1:200
	ds_read2_b32 v[14:15], v16 offset0:201 offset1:202
	s_waitcnt lgkmcnt(0)
	v_pk_add_f32 v[78:79], v[78:79], v[6:7]
	v_pk_add_f32 v[76:77], v[76:77], v[4:5]
	v_pk_add_f32 v[74:75], v[74:75], v[2:3]
	v_pk_add_f32 v[72:73], v[72:73], v[0:1]
	v_pk_add_f32 v[70:71], v[70:71], v[14:15]
	v_pk_add_f32 v[68:69], v[68:69], v[12:13]
	v_pk_add_f32 v[66:67], v[66:67], v[10:11]
	v_pk_add_f32 v[64:65], v[64:65], v[8:9]
	ds_read2_b32 v[0:1], v16 offset0:239 offset1:240
	ds_read2_b32 v[2:3], v16 offset0:241 offset1:242
	ds_read2_b32 v[4:5], v16 offset0:247 offset1:248
	ds_read2_b32 v[6:7], v16 offset0:249 offset1:250
	ds_read2_b32 v[8:9], v16 offset0:223 offset1:224
	ds_read2_b32 v[10:11], v16 offset0:225 offset1:226
	ds_read2_b32 v[12:13], v16 offset0:231 offset1:232
	ds_read2_b32 v[14:15], v16 offset0:233 offset1:234
	s_waitcnt lgkmcnt(0)
	v_pk_add_f32 v[94:95], v[94:95], v[6:7]
	v_pk_add_f32 v[92:93], v[92:93], v[4:5]
	v_pk_add_f32 v[90:91], v[90:91], v[2:3]
	v_pk_add_f32 v[88:89], v[88:89], v[0:1]
	v_pk_add_f32 v[86:87], v[86:87], v[14:15]
	v_pk_add_f32 v[84:85], v[84:85], v[12:13]
	v_pk_add_f32 v[82:83], v[82:83], v[10:11]
	v_pk_add_f32 v[80:81], v[80:81], v[8:9]
.LBB0_373:
	v_max_f32_e32 v0, v65, v65
	v_max_f32_e32 v1, v64, v64
	v_max_f32_e32 v0, v1, v0
	v_max3_f32 v0, v0, v66, v67
	v_max3_f32 v0, v0, v68, v69
	v_max3_f32 v0, v0, v70, v71
	v_max3_f32 v0, v0, v72, v73
	v_max3_f32 v0, v0, v74, v75
	v_max3_f32 v0, v0, v76, v77
	v_max3_f32 v0, v0, v78, v79
	v_max3_f32 v0, v0, v80, v81
	v_max3_f32 v0, v0, v82, v83
	v_max3_f32 v0, v0, v84, v85
	v_max3_f32 v0, v0, v86, v87
	v_max3_f32 v0, v0, v88, v89
	v_max3_f32 v0, v0, v90, v91
	v_max3_f32 v0, v0, v92, v93
	v_max3_f32 v0, v0, v94, v95
	v_mov_b32_e32 v1, v0
	s_nop 1
	v_permlane32_swap_b32_e32 v0, v1
	v_max_f32_e32 v1, v1, v1
	v_max_f32_e32 v0, v0, v0
	v_max_f32_e32 v189, v0, v1
	v_xor_b32_e32 v232, 0x80000000, v189
	v_mov_b32_e32 v233, v232
	v_mov_b32_e32 v234, v232
	v_mov_b32_e32 v235, v232
	v_mov_b32_e32 v236, v232
	v_mov_b32_e32 v237, v232
	v_mov_b32_e32 v238, v232
	v_mov_b32_e32 v239, v232
	v_mov_b32_e32 v240, v232
	v_mov_b32_e32 v241, v232
	v_mov_b32_e32 v242, v232
	v_mov_b32_e32 v243, v232
	v_mov_b32_e32 v244, v232
	v_mov_b32_e32 v245, v232
	v_mov_b32_e32 v246, v232
	v_mov_b32_e32 v247, v232
	v_sub_f32_e32 v0, v80, v189
	v_sub_f32_e32 v1, v81, v189
	v_sub_f32_e32 v2, v82, v189
	v_sub_f32_e32 v3, v83, v189
	v_sub_f32_e32 v4, v84, v189
	v_sub_f32_e32 v5, v85, v189
	v_sub_f32_e32 v6, v86, v189
	v_sub_f32_e32 v7, v87, v189
	v_sub_f32_e32 v8, v88, v189
	v_sub_f32_e32 v9, v89, v189
	v_sub_f32_e32 v10, v90, v189
	v_sub_f32_e32 v11, v91, v189
	v_sub_f32_e32 v12, v92, v189
	v_sub_f32_e32 v13, v93, v189
	v_sub_f32_e32 v14, v94, v189
	v_sub_f32_e32 v15, v95, v189
	v_sub_f32_e32 v16, v64, v189
	v_sub_f32_e32 v17, v65, v189
	v_sub_f32_e32 v18, v66, v189
	v_sub_f32_e32 v19, v67, v189
	v_sub_f32_e32 v20, v68, v189
	v_sub_f32_e32 v21, v69, v189
	v_sub_f32_e32 v22, v70, v189
	v_sub_f32_e32 v23, v71, v189
	v_sub_f32_e32 v24, v72, v189
	v_sub_f32_e32 v25, v73, v189
	v_sub_f32_e32 v26, v74, v189
	v_sub_f32_e32 v27, v75, v189
	v_sub_f32_e32 v28, v76, v189
	v_sub_f32_e32 v29, v77, v189
	v_sub_f32_e32 v30, v78, v189
	v_sub_f32_e32 v31, v79, v189
	v_exp_f32_e32 v112, v16
	v_exp_f32_e32 v113, v17
	v_exp_f32_e32 v114, v18
	v_exp_f32_e32 v115, v19
	v_exp_f32_e32 v116, v20
	v_exp_f32_e32 v117, v21
	v_exp_f32_e32 v118, v22
	v_exp_f32_e32 v119, v23
	v_exp_f32_e32 v120, v24
	v_exp_f32_e32 v121, v25
	v_exp_f32_e32 v122, v26
	v_exp_f32_e32 v123, v27
	v_exp_f32_e32 v124, v28
	v_exp_f32_e32 v125, v29
	v_exp_f32_e32 v126, v30
	v_exp_f32_e32 v127, v31
	v_exp_f32_e32 v96, v0
	v_exp_f32_e32 v97, v1
	v_exp_f32_e32 v98, v2
	v_exp_f32_e32 v99, v3
	v_exp_f32_e32 v100, v4
	v_exp_f32_e32 v101, v5
	v_exp_f32_e32 v102, v6
	v_exp_f32_e32 v103, v7
	v_exp_f32_e32 v104, v8
	v_exp_f32_e32 v105, v9
	v_exp_f32_e32 v106, v10
	v_exp_f32_e32 v107, v11
	v_exp_f32_e32 v108, v12
	v_exp_f32_e32 v109, v13
	v_exp_f32_e32 v110, v14
	v_exp_f32_e32 v111, v15
	s_waitcnt vmcnt(4)
	s_barrier
; DI void diff_core(unsigned char* smem, const u16* qptr, const u16* kbase, const u16* vtbase, int vld,
;                   int ntb, int ntw, int nvalid, int ks0, const float* lut, int qpos, bool active, bool grpB,
;                   f32x16 (&O)[4], float& l_out) {
;     ...
;   auto qk = [&](int slot) {
;     if (grpB) __builtin_amdgcn_s_setprio(2); else __builtin_amdgcn_s_setprio(1);
;     const float ini = -m;
; #pragma unroll
;     for (int kb = 0; kb < 2; ++kb)
; #pragma unroll
;       for (int e = 0; e < 16; ++e) S[kb][e] = ini;
;     const LAS unsigned char* b = lds + slot * D_SLOT;
;     bf16x8 kf[4][2];
; #pragma unroll
;     ...
;   auto pv = [&](int slot) {
;     if (grpB) __builtin_amdgcn_s_setprio(2); else __builtin_amdgcn_s_setprio(1);
;     const LAS unsigned char* b = lds + slot * D_SLOT;
;     bf16x8 va[4], vb[4];
; #pragma unroll
;     for (int tt = 0; tt < 4; ++tt) va[tt] = *reinterpret_cast<const LAS bf16x8*>(b + voff[0] + tt * 32 * 128);
; #pragma unroll
;     for (int tt = 0; tt < 4; ++tt) vb[tt] = *reinterpret_cast<const LAS bf16x8*>(b + voff[1] + tt * 32 * 128);
;     {
;       const bf16x8 pf = __builtin_bit_cast(bf16x8, P[0]);
; #pragma unroll
;       for (int tt = 0; tt < 4; ++tt) O[tt] = MFMA(va[tt], pf, O[tt]);
;     }
; #pragma unroll
;     for (int tt = 0; tt < 4; ++tt) va[tt] = *reinterpret_cast<const LAS bf16x8*>(b + voff[2] + tt * 32 * 128);
;     {
;       const bf16x8 pf = __builtin_bit_cast(bf16x8, P[1]);
; #pragma unroll
;       for (int tt = 0; tt < 4; ++tt) O[tt] = MFMA(vb[tt], pf, O[tt]);
;     }
; #pragma unroll
;     for (int tt = 0; tt < 4; ++tt) vb[tt] = *reinterpret_cast<const LAS bf16x8*>(b + voff[3] + tt * 32 * 128);
;     {
;       const bf16x8 pf = __builtin_bit_cast(bf16x8, P[2]);
; #pragma unroll
;       for (int tt = 0; tt < 4; ++tt) O[tt] = MFMA(va[tt], pf, O[tt]);
;     }
;     {
;       const bf16x8 pf = __builtin_bit_cast(bf16x8, P[3]);
; #pragma unroll
;       for (int tt = 0; tt < 4; ++tt) O[tt] = MFMA(vb[tt], pf, O[tt]);
;     }
;     __builtin_amdgcn_sched_group_barrier(0x100, 8, 0);
;     __builtin_amdgcn_sched_group_barrier(0x008, 4, 0);
;     __builtin_amdgcn_sched_group_barrier(0x100, 4, 0);
;     __builtin_amdgcn_sched_group_barrier(0x008, 4, 0);
;     __builtin_amdgcn_sched_group_barrier(0x100, 4, 0);
;     __builtin_amdgcn_sched_group_barrier(0x008, 8, 0);
;     __builtin_amdgcn_s_setprio(0);
;   };
	s_min_u32 s63, s58, 3
	s_add_i32 m0, s6, 0x18000
	s_lshl_b32 s0, s63, 17
	s_add_u32 s0, s14, s0
	s_addc_u32 s1, s15, 0
	v_lshl_add_u64 v[0:1], s[0:1], 0, v[162:163]
	s_lshl_b32 s63, s63, 7
	global_load_lds_dwordx4 v[0:1], off
	s_add_i32 m0, s6, 0x1a000
	v_lshl_add_u64 v[0:1], s[0:1], 0, v[170:171]
	s_add_u32 s0, s20, s63
	s_addc_u32 s1, s21, 0
	global_load_lds_dwordx4 v[0:1], off
	v_lshl_add_u64 v[0:1], s[0:1], 0, v[166:167]
	s_add_i32 m0, s6, 0x1c000
	s_nop 0
	global_load_lds_dwordx4 v[0:1], off
	v_lshl_add_u64 v[0:1], s[0:1], 0, v[168:169]
	s_add_i32 m0, s6, 0x1e000
	s_nop 0
	global_load_lds_dwordx4 v[0:1], off
	v_cvt_pk_bf16_f32 v144, v112, v113
	v_cvt_pk_bf16_f32 v145, v114, v115
	v_cvt_pk_bf16_f32 v146, v116, v117
	v_cvt_pk_bf16_f32 v147, v118, v119
	v_cvt_pk_bf16_f32 v148, v120, v121
	v_cvt_pk_bf16_f32 v149, v122, v123
	v_cvt_pk_bf16_f32 v150, v124, v125
	v_cvt_pk_bf16_f32 v151, v126, v127
	v_cvt_pk_bf16_f32 v152, v96, v97
	v_cvt_pk_bf16_f32 v153, v98, v99
	v_cvt_pk_bf16_f32 v154, v100, v101
	v_cvt_pk_bf16_f32 v155, v102, v103
	v_cvt_pk_bf16_f32 v156, v104, v105
	v_cvt_pk_bf16_f32 v157, v106, v107
	v_cvt_pk_bf16_f32 v158, v108, v109
	v_cvt_pk_bf16_f32 v159, v110, v111
	s_setprio 2
	v_add_u32_e32 v188, v188, v184
	v_add_u32_e32 v12, 0, v188
	ds_read_b128 v[0:3], v12 offset:16384
	ds_read_b128 v[4:7], v12 offset:20480
	ds_read_b128 v[8:11], v12 offset:24576
	ds_read_b128 v[12:15], v12 offset:28672
	v_add_u32_e32 v187, v187, v184
	v_add_u32_e32 v16, 0, v187
	ds_read_b128 v[64:67], v16 offset:16384
	ds_read_b128 v[68:71], v16 offset:20480
	ds_read_b128 v[72:75], v16 offset:24576
	ds_read_b128 v[76:79], v16 offset:28672
	s_waitcnt lgkmcnt(0)
	v_mfma_f32_32x32x16_bf16 v[48:63], v[0:3], v[144:147], 0
	v_add_u32_e32 v186, v186, v184
	v_add_u32_e32 v92, 0, v186
	v_add_u32_e32 v184, v185, v184
	v_mfma_f32_32x32x16_bf16 v[32:47], v[4:7], v[144:147], 0
	v_mfma_f32_32x32x16_bf16 v[16:31], v[8:11], v[144:147], 0
	v_mfma_f32_32x32x16_bf16 v[0:15], v[12:15], v[144:147], 0
	ds_read_b128 v[80:83], v92 offset:16384
	ds_read_b128 v[84:87], v92 offset:20480
	ds_read_b128 v[88:91], v92 offset:24576
	ds_read_b128 v[92:95], v92 offset:28672
	v_mfma_f32_32x32x16_bf16 v[48:63], v[64:67], v[148:151], v[48:63]
	v_mfma_f32_32x32x16_bf16 v[32:47], v[68:71], v[148:151], v[32:47]
	v_mfma_f32_32x32x16_bf16 v[16:31], v[72:75], v[148:151], v[16:31]
	v_mfma_f32_32x32x16_bf16 v[0:15], v[76:79], v[148:151], v[0:15]
	v_add_u32_e32 v76, 0, v184
	ds_read_b128 v[64:67], v76 offset:16384
	ds_read_b128 v[68:71], v76 offset:20480
	ds_read_b128 v[72:75], v76 offset:24576
	ds_read_b128 v[76:79], v76 offset:28672
	s_waitcnt lgkmcnt(0)
	v_mfma_f32_32x32x16_bf16 v[48:63], v[80:83], v[152:155], v[48:63]
	v_mfma_f32_32x32x16_bf16 v[32:47], v[84:87], v[152:155], v[32:47]
	v_mfma_f32_32x32x16_bf16 v[16:31], v[88:91], v[152:155], v[16:31]
	v_mfma_f32_32x32x16_bf16 v[0:15], v[92:95], v[152:155], v[0:15]
	v_mfma_f32_32x32x16_bf16 v[48:63], v[64:67], v[156:159], v[48:63]
	v_mfma_f32_32x32x16_bf16 v[32:47], v[68:71], v[156:159], v[32:47]
	v_mfma_f32_32x32x16_bf16 v[16:31], v[72:75], v[156:159], v[16:31]
	v_mfma_f32_32x32x16_bf16 v[0:15], v[76:79], v[156:159], v[0:15]
	s_setprio 0
	s_cmp_gt_u32 s16, 1
	s_cbranch_scc0 .LBB0_375
	s_setprio 2
	v_add_u32_e32 v80, 0, v177
	ds_read_b128 v[196:199], v80 offset:32768
	ds_read_b128 v[200:203], v80 offset:40960
	v_add_u32_e32 v80, 0, v178
	ds_read_b128 v[204:207], v80 offset:32768
	ds_read_b128 v[208:211], v80 offset:40960
	v_add_u32_e32 v80, 0, v179
	ds_read_b128 v[212:215], v80 offset:32768
	ds_read_b128 v[216:219], v80 offset:40960
	v_add_u32_e32 v80, 0, v180
	ds_read_b128 v[220:223], v80 offset:32768
	ds_read_b128 v[224:227], v80 offset:40960
	s_waitcnt lgkmcnt(0)
	v_mfma_f32_32x32x16_bf16 v[80:95], v[196:199], v[128:131], v[232:247]
	v_mfma_f32_32x32x16_bf16 v[64:79], v[200:203], v[128:131], v[232:247]
	v_mfma_f32_32x32x16_bf16 v[80:95], v[204:207], v[132:135], v[80:95]
	v_mfma_f32_32x32x16_bf16 v[64:79], v[208:211], v[132:135], v[64:79]
	v_mfma_f32_32x32x16_bf16 v[80:95], v[212:215], v[136:139], v[80:95]
	v_mfma_f32_32x32x16_bf16 v[64:79], v[216:219], v[136:139], v[64:79]
	v_mfma_f32_32x32x16_bf16 v[80:95], v[220:223], v[140:143], v[80:95]
	v_mfma_f32_32x32x16_bf16 v[64:79], v[224:227], v[140:143], v[64:79]
	s_setprio 0
	s_branch .LBB0_376

; DI int crow(int i, int hh) { return (i & 3) + 8 * (i >> 2) + 4 * hh; }
; DI void diff_core(unsigned char* smem, const u16* qptr, const u16* kbase, const u16* vtbase, int vld,
;                   int ntb, int ntw, int nvalid, int ks0, const float* lut, int qpos, bool active, bool grpB,
;                   f32x16 (&O)[4], float& l_out) {
;     ...
;     if (lut != nullptr && t >= ntw - 3) {
;       const int base = t * 64 - qpos + 191;
; #pragma unroll
;       for (int kb = 0; kb < 2; ++kb)
; #pragma unroll
;         for (int i = 0; i < 16; ++i) S[kb][i] += lut[base + kb * 32 + crow(i, hh)];
;     }
;     if (t == ntw - 1 && nvalid < 64) {
; #pragma unroll
;       for (int kb = 0; kb < 2; ++kb)
; #pragma unroll
;         for (int i = 0; i < 16; ++i)
;           if (kb * 32 + crow(i, hh) >= nvalid) S[kb][i] = -1e30f;
;     }
;     float mx = S[0][0];
; #pragma unroll
;     for (int kb = 0; kb < 2; ++kb)
; #pragma unroll
;       for (int i = 0; i < 16; ++i) mx = fmaxf(mx, S[kb][i]);
;     {
;       const unsigned um = __float_as_uint(mx);
;       const auto sw = __builtin_amdgcn_permlane32_swap(um, um, false, false);
;       mx = fmaxf(__uint_as_float(sw[0]), __uint_as_float(sw[1]));
;     }
;     if (t == 0) {
;       m = mx;
; #pragma unroll
;       for (int kb = 0; kb < 2; ++kb)
; #pragma unroll
;         for (int i = 0; i < 16; ++i) S[kb][i] -= mx;
;     } else if (__any(mx > 8.f)) {
;       const float d = fmaxf(mx, 0.f);
;       const float alpha = __builtin_amdgcn_exp2f(-d);
;       m += d;
;       l *= alpha;
; #pragma unroll
;       for (int tt = 0; tt < 4; ++tt)
; #pragma unroll
;         for (int e = 0; e < 16; ++e) O[tt][e] *= alpha;
; #pragma unroll
;       for (int kb = 0; kb < 2; ++kb)
; #pragma unroll
;         for (int i = 0; i < 16; ++i) S[kb][i] -= d;
;     }
.LBB0_378:
	s_add_i32 s64, s62, 0x101
	s_cmp_lt_u32 s64, s16
	s_cselect_b64 s[0:1], -1, 0
	s_cmp_ge_u32 s64, s16
	s_cbranch_scc1 .LBB0_384
	s_cmp_lt_i32 s64, s17
	s_cbranch_scc1 .LBB0_381
	ds_read2_b32 v[98:99], v96 offset1:1
	ds_read2_b32 v[100:101], v96 offset0:16 offset1:17
	ds_read2_b32 v[102:103], v96 offset0:18 offset1:19
	ds_read2_b32 v[104:105], v96 offset0:24 offset1:25
	ds_read2_b32 v[106:107], v96 offset0:26 offset1:27
	ds_read2_b32 v[108:109], v96 offset0:2 offset1:3
	ds_read2_b32 v[110:111], v96 offset0:8 offset1:9
	ds_read2_b32 v[112:113], v96 offset0:10 offset1:11
	s_waitcnt lgkmcnt(0)
	v_pk_add_f32 v[80:81], v[80:81], v[98:99]
	v_pk_add_f32 v[94:95], v[94:95], v[106:107]
	v_pk_add_f32 v[92:93], v[92:93], v[104:105]
	v_pk_add_f32 v[90:91], v[90:91], v[102:103]
	v_pk_add_f32 v[88:89], v[88:89], v[100:101]
	v_pk_add_f32 v[86:87], v[86:87], v[112:113]
	v_pk_add_f32 v[84:85], v[84:85], v[110:111]
	v_pk_add_f32 v[82:83], v[82:83], v[108:109]
	ds_read2_b32 v[98:99], v96 offset0:32 offset1:33
	ds_read2_b32 v[100:101], v96 offset0:48 offset1:49
	ds_read2_b32 v[102:103], v96 offset0:50 offset1:51
	ds_read2_b32 v[104:105], v96 offset0:56 offset1:57
	ds_read2_b32 v[106:107], v96 offset0:58 offset1:59
	ds_read2_b32 v[108:109], v96 offset0:34 offset1:35
	ds_read2_b32 v[110:111], v96 offset0:40 offset1:41
	ds_read2_b32 v[112:113], v96 offset0:42 offset1:43
	s_waitcnt lgkmcnt(0)
	v_pk_add_f32 v[64:65], v[64:65], v[98:99]
	v_pk_add_f32 v[78:79], v[78:79], v[106:107]
	v_pk_add_f32 v[76:77], v[76:77], v[104:105]
	v_pk_add_f32 v[74:75], v[74:75], v[102:103]
	v_pk_add_f32 v[72:73], v[72:73], v[100:101]
	v_pk_add_f32 v[70:71], v[70:71], v[112:113]
	v_pk_add_f32 v[68:69], v[68:69], v[110:111]
	v_pk_add_f32 v[66:67], v[66:67], v[108:109]
.LBB0_381:
	v_max_f32_e32 v97, v81, v81
	v_max_f32_e32 v98, v80, v80
	v_max_f32_e32 v97, v98, v97
	v_max3_f32 v97, v97, v82, v83
	v_max3_f32 v97, v97, v84, v85
	v_max3_f32 v97, v97, v86, v87
	v_max3_f32 v97, v97, v88, v89
	v_max3_f32 v97, v97, v90, v91
	v_max3_f32 v97, v97, v92, v93
	v_max3_f32 v97, v97, v94, v95
	v_max3_f32 v97, v97, v64, v65
	v_max3_f32 v97, v97, v66, v67
	v_max3_f32 v97, v97, v68, v69
	v_max3_f32 v97, v97, v70, v71
	v_max3_f32 v97, v97, v72, v73
	v_max3_f32 v97, v97, v74, v75
	v_max3_f32 v97, v97, v76, v77
	v_max3_f32 v97, v97, v78, v79
	v_mov_b32_e32 v98, v97
	s_nop 1
	v_permlane32_swap_b32_e32 v97, v98
	v_max_f32_e32 v97, v97, v98
	v_cmp_lt_f32_e32 vcc, s23, v97
	s_cbranch_vccz .LBB0_383
	v_max_f32_e32 v97, v97, v97
	v_max_f32_e32 v98, 0, v97
	v_exp_f32_e64 v100, -v98
	v_add_f32_e32 v189, v189, v98
	v_xor_b32_e32 v232, 0x80000000, v189
	v_mov_b32_e32 v233, v232
	v_mov_b32_e32 v234, v232
	v_mov_b32_e32 v235, v232
	v_mov_b32_e32 v236, v232
	v_mov_b32_e32 v237, v232
	v_mov_b32_e32 v238, v232
	v_mov_b32_e32 v239, v232
	v_mov_b32_e32 v240, v232
	v_mov_b32_e32 v241, v232
	v_mov_b32_e32 v242, v232
	v_mov_b32_e32 v243, v232
	v_mov_b32_e32 v244, v232
	v_mov_b32_e32 v245, v232
	v_mov_b32_e32 v246, v232
	v_mov_b32_e32 v247, v232
	v_pk_add_f32 v[80:81], v[80:81], v[98:99] op_sel_hi:[1,0] neg_lo:[0,1] neg_hi:[0,1]
	v_pk_add_f32 v[82:83], v[82:83], v[98:99] op_sel_hi:[1,0] neg_lo:[0,1] neg_hi:[0,1]
	v_pk_mul_f32 v[14:15], v[14:15], v[100:101] op_sel_hi:[1,0]
	v_pk_mul_f32 v[12:13], v[12:13], v[100:101] op_sel_hi:[1,0]
	v_pk_mul_f32 v[10:11], v[10:11], v[100:101] op_sel_hi:[1,0]
	v_pk_mul_f32 v[8:9], v[8:9], v[100:101] op_sel_hi:[1,0]
	v_pk_mul_f32 v[6:7], v[6:7], v[100:101] op_sel_hi:[1,0]
	v_pk_mul_f32 v[4:5], v[4:5], v[100:101] op_sel_hi:[1,0]
	v_pk_mul_f32 v[2:3], v[2:3], v[100:101] op_sel_hi:[1,0]
	v_pk_mul_f32 v[0:1], v[0:1], v[100:101] op_sel_hi:[1,0]
	v_pk_mul_f32 v[30:31], v[30:31], v[100:101] op_sel_hi:[1,0]
	v_pk_mul_f32 v[28:29], v[28:29], v[100:101] op_sel_hi:[1,0]
	v_pk_mul_f32 v[26:27], v[26:27], v[100:101] op_sel_hi:[1,0]
	v_pk_mul_f32 v[24:25], v[24:25], v[100:101] op_sel_hi:[1,0]
	v_pk_mul_f32 v[22:23], v[22:23], v[100:101] op_sel_hi:[1,0]
	v_pk_mul_f32 v[20:21], v[20:21], v[100:101] op_sel_hi:[1,0]
	v_pk_mul_f32 v[18:19], v[18:19], v[100:101] op_sel_hi:[1,0]
	v_pk_mul_f32 v[16:17], v[16:17], v[100:101] op_sel_hi:[1,0]
	v_pk_mul_f32 v[46:47], v[46:47], v[100:101] op_sel_hi:[1,0]
	v_pk_mul_f32 v[44:45], v[44:45], v[100:101] op_sel_hi:[1,0]
	v_pk_mul_f32 v[42:43], v[42:43], v[100:101] op_sel_hi:[1,0]
	v_pk_mul_f32 v[40:41], v[40:41], v[100:101] op_sel_hi:[1,0]
	v_pk_mul_f32 v[38:39], v[38:39], v[100:101] op_sel_hi:[1,0]
	v_pk_mul_f32 v[36:37], v[36:37], v[100:101] op_sel_hi:[1,0]
	v_pk_mul_f32 v[34:35], v[34:35], v[100:101] op_sel_hi:[1,0]
	v_pk_mul_f32 v[32:33], v[32:33], v[100:101] op_sel_hi:[1,0]
	v_pk_mul_f32 v[62:63], v[62:63], v[100:101] op_sel_hi:[1,0]
	v_pk_mul_f32 v[60:61], v[60:61], v[100:101] op_sel_hi:[1,0]
	v_pk_mul_f32 v[58:59], v[58:59], v[100:101] op_sel_hi:[1,0]
	v_pk_mul_f32 v[56:57], v[56:57], v[100:101] op_sel_hi:[1,0]
	v_pk_mul_f32 v[54:55], v[54:55], v[100:101] op_sel_hi:[1,0]
	v_pk_mul_f32 v[52:53], v[52:53], v[100:101] op_sel_hi:[1,0]
	v_pk_mul_f32 v[50:51], v[50:51], v[100:101] op_sel_hi:[1,0]
	v_pk_mul_f32 v[48:49], v[48:49], v[100:101] op_sel_hi:[1,0]
	v_mul_f32_e32 v181, v181, v100
	v_pk_add_f32 v[84:85], v[84:85], v[98:99] op_sel_hi:[1,0] neg_lo:[0,1] neg_hi:[0,1]
	v_pk_add_f32 v[86:87], v[86:87], v[98:99] op_sel_hi:[1,0] neg_lo:[0,1] neg_hi:[0,1]
	v_pk_add_f32 v[88:89], v[88:89], v[98:99] op_sel_hi:[1,0] neg_lo:[0,1] neg_hi:[0,1]
	v_pk_add_f32 v[90:91], v[90:91], v[98:99] op_sel_hi:[1,0] neg_lo:[0,1] neg_hi:[0,1]
	v_pk_add_f32 v[92:93], v[92:93], v[98:99] op_sel_hi:[1,0] neg_lo:[0,1] neg_hi:[0,1]
	v_pk_add_f32 v[94:95], v[94:95], v[98:99] op_sel_hi:[1,0] neg_lo:[0,1] neg_hi:[0,1]
	v_pk_add_f32 v[64:65], v[64:65], v[98:99] op_sel_hi:[1,0] neg_lo:[0,1] neg_hi:[0,1]
	v_pk_add_f32 v[66:67], v[66:67], v[98:99] op_sel_hi:[1,0] neg_lo:[0,1] neg_hi:[0,1]
	v_pk_add_f32 v[68:69], v[68:69], v[98:99] op_sel_hi:[1,0] neg_lo:[0,1] neg_hi:[0,1]
	v_pk_add_f32 v[70:71], v[70:71], v[98:99] op_sel_hi:[1,0] neg_lo:[0,1] neg_hi:[0,1]
	v_pk_add_f32 v[72:73], v[72:73], v[98:99] op_sel_hi:[1,0] neg_lo:[0,1] neg_hi:[0,1]
	v_pk_add_f32 v[74:75], v[74:75], v[98:99] op_sel_hi:[1,0] neg_lo:[0,1] neg_hi:[0,1]
	v_pk_add_f32 v[76:77], v[76:77], v[98:99] op_sel_hi:[1,0] neg_lo:[0,1] neg_hi:[0,1]
	v_pk_add_f32 v[78:79], v[78:79], v[98:99] op_sel_hi:[1,0] neg_lo:[0,1] neg_hi:[0,1]
; DI void diff_core(unsigned char* smem, const u16* qptr, const u16* kbase, const u16* vtbase, int vld,
;                   int ntb, int ntw, int nvalid, int ks0, const float* lut, int qpos, bool active, bool grpB,
;                   f32x16 (&O)[4], float& l_out) {
;     ...
;   auto pv = [&](int slot) {
;     if (grpB) __builtin_amdgcn_s_setprio(2); else __builtin_amdgcn_s_setprio(1);
;     const LAS unsigned char* b = lds + slot * D_SLOT;
;     bf16x8 va[4], vb[4];
; #pragma unroll
;     for (int tt = 0; tt < 4; ++tt) va[tt] = *reinterpret_cast<const LAS bf16x8*>(b + voff[0] + tt * 32 * 128);
; #pragma unroll
;     for (int tt = 0; tt < 4; ++tt) vb[tt] = *reinterpret_cast<const LAS bf16x8*>(b + voff[1] + tt * 32 * 128);
;     {
;       const bf16x8 pf = __builtin_bit_cast(bf16x8, P[0]);
; #pragma unroll
;       for (int tt = 0; tt < 4; ++tt) O[tt] = MFMA(va[tt], pf, O[tt]);
;     }
; #pragma unroll
;     for (int tt = 0; tt < 4; ++tt) va[tt] = *reinterpret_cast<const LAS bf16x8*>(b + voff[2] + tt * 32 * 128);
;     {
;       const bf16x8 pf = __builtin_bit_cast(bf16x8, P[1]);
; #pragma unroll
;       for (int tt = 0; tt < 4; ++tt) O[tt] = MFMA(vb[tt], pf, O[tt]);
;     }
; #pragma unroll
;     for (int tt = 0; tt < 4; ++tt) vb[tt] = *reinterpret_cast<const LAS bf16x8*>(b + voff[3] + tt * 32 * 128);
;     {
;       const bf16x8 pf = __builtin_bit_cast(bf16x8, P[2]);
; #pragma unroll
;       for (int tt = 0; tt < 4; ++tt) O[tt] = MFMA(va[tt], pf, O[tt]);
;     }
;     {
;       const bf16x8 pf = __builtin_bit_cast(bf16x8, P[3]);
; #pragma unroll
;       for (int tt = 0; tt < 4; ++tt) O[tt] = MFMA(vb[tt], pf, O[tt]);
;     }
;     __builtin_amdgcn_sched_group_barrier(0x100, 8, 0);
;     __builtin_amdgcn_sched_group_barrier(0x008, 4, 0);
;     __builtin_amdgcn_sched_group_barrier(0x100, 4, 0);
;     __builtin_amdgcn_sched_group_barrier(0x008, 4, 0);
;     __builtin_amdgcn_sched_group_barrier(0x100, 4, 0);
;     __builtin_amdgcn_sched_group_barrier(0x008, 8, 0);
;     __builtin_amdgcn_s_setprio(0);
;   };
;     ...
;     float ps = 0.f;
; #pragma unroll
;     for (int kb = 0; kb < 2; ++kb)
; #pragma unroll
;       for (int i = 0; i < 16; ++i) {
;         const float pe = __builtin_amdgcn_exp2f(S[kb][i]);
;         S[kb][i] = pe;
;         ps += pe;
;       }
;     l += ps;
; #pragma unroll
;     for (int kb = 0; kb < 2; ++kb)
; #pragma unroll
.LBB0_383:
	v_exp_f32_e32 v80, v80
	v_exp_f32_e32 v81, v81
	v_exp_f32_e32 v82, v82
	v_exp_f32_e32 v83, v83
	v_exp_f32_e32 v84, v84
	v_exp_f32_e32 v85, v85
	v_exp_f32_e32 v86, v86
	v_exp_f32_e32 v87, v87
	v_exp_f32_e32 v88, v88
	v_exp_f32_e32 v89, v89
	v_exp_f32_e32 v90, v90
	v_exp_f32_e32 v91, v91
	v_exp_f32_e32 v92, v92
	v_exp_f32_e32 v93, v93
	v_exp_f32_e32 v94, v94
	v_exp_f32_e32 v95, v95
	v_exp_f32_e32 v64, v64
	v_exp_f32_e32 v65, v65
	v_exp_f32_e32 v66, v66
	v_exp_f32_e32 v67, v67
	v_exp_f32_e32 v68, v68
	v_exp_f32_e32 v69, v69
	v_exp_f32_e32 v70, v70
	v_exp_f32_e32 v71, v71
	v_exp_f32_e32 v72, v72
	v_exp_f32_e32 v73, v73
	v_exp_f32_e32 v74, v74
	v_exp_f32_e32 v75, v75
	v_exp_f32_e32 v76, v76
	v_exp_f32_e32 v77, v77
	v_exp_f32_e32 v78, v78
	v_exp_f32_e32 v79, v79
.LBB0_384:
	s_waitcnt vmcnt(4)
	s_barrier
	s_add_i32 s65, s62, 0x104
	s_min_i32 s65, s65, s58
	s_add_i32 s66, s59, 0x8000
	s_and_b32 s66, s66, 0x18000
	s_add_i32 s85, s6, s66
	s_lshl_b32 s66, s65, 6
	s_ashr_i32 s67, s66, 31
	s_lshl_b64 s[86:87], s[66:67], 11
	s_add_u32 s86, s14, s86
	s_addc_u32 s87, s15, s87
	s_lshl_b64 s[66:67], s[66:67], 1
	s_add_i32 s65, s85, 0x2000
	s_add_u32 s66, s20, s66
	s_mov_b32 m0, s85
	s_addc_u32 s67, s21, s67
	s_add_i32 s88, s85, 0x4000
	global_load_lds_dwordx4 v162, s[86:87]
	s_mov_b32 m0, s65
	s_add_i32 s89, s85, 0x6000
	global_load_lds_dwordx4 v170, s[86:87]
	s_mov_b32 m0, s88
	s_nop 0
	global_load_lds_dwordx4 v166, s[66:67]
	s_mov_b32 m0, s89
	s_nop 0
	global_load_lds_dwordx4 v168, s[66:67]
	s_andn2_b64 vcc, exec, s[0:1]
	s_cbranch_vccnz .LBB0_386
	s_setprio 2
	s_add_i32 s0, s59, 0xffff0000
	s_and_b32 s0, s0, 0x18000
	v_add_u32_e32 v97, s0, v188
	ds_read_b128 v[98:101], v97 offset:16384
	ds_read_b128 v[102:105], v97 offset:20480
	ds_read_b128 v[106:109], v97 offset:24576
	ds_read_b128 v[110:113], v97 offset:28672
	v_add_u32_e32 v126, s0, v187
	ds_read_b128 v[114:117], v126 offset:16384
	ds_read_b128 v[118:121], v126 offset:20480
	ds_read_b128 v[122:125], v126 offset:24576
	ds_read_b128 v[196:199], v126 offset:28672
	s_add_i32 s67, s59, 0xffff8000
	s_and_b32 s67, s67, 0x18000
	v_cvt_pk_bf16_f32 v144, v80, v81
	v_cvt_pk_bf16_f32 v145, v82, v83
	v_cvt_pk_bf16_f32 v146, v84, v85
	v_cvt_pk_bf16_f32 v147, v86, v87
	v_add_f32_e32 v250, v81, v80
	v_add_f32_e32 v250, v82, v250
	s_waitcnt lgkmcnt(0)
	v_mfma_f32_32x32x16_bf16 v[48:63], v[98:101], v[144:147], v[48:63]
	v_cvt_pk_bf16_f32 v148, v88, v89
	v_add_f32_e32 v250, v83, v250
	v_add_f32_e32 v250, v84, v250
	v_mfma_f32_32x32x16_bf16 v[32:47], v[102:105], v[144:147], v[32:47]
	v_cvt_pk_bf16_f32 v149, v90, v91
	v_add_f32_e32 v250, v85, v250
	v_add_f32_e32 v250, v86, v250
	v_mfma_f32_32x32x16_bf16 v[16:31], v[106:109], v[144:147], v[16:31]
	v_cvt_pk_bf16_f32 v150, v92, v93
	v_add_f32_e32 v250, v87, v250
	v_add_f32_e32 v250, v88, v250
	v_mfma_f32_32x32x16_bf16 v[0:15], v[110:113], v[144:147], v[0:15]
	v_cvt_pk_bf16_f32 v151, v94, v95
	v_add_f32_e32 v250, v89, v250
	v_add_f32_e32 v250, v90, v250
	v_add_u32_e32 v97, s0, v186
	ds_read_b128 v[98:101], v97 offset:16384
	ds_read_b128 v[102:105], v97 offset:20480
	ds_read_b128 v[106:109], v97 offset:24576
	ds_read_b128 v[110:113], v97 offset:28672
	v_mfma_f32_32x32x16_bf16 v[48:63], v[114:117], v[148:151], v[48:63]
	v_cvt_pk_bf16_f32 v152, v64, v65
	v_add_f32_e32 v250, v91, v250
	v_add_f32_e32 v250, v92, v250
	v_mfma_f32_32x32x16_bf16 v[32:47], v[118:121], v[148:151], v[32:47]
	v_cvt_pk_bf16_f32 v153, v66, v67
	v_add_f32_e32 v250, v93, v250
	v_add_f32_e32 v250, v94, v250
	v_mfma_f32_32x32x16_bf16 v[16:31], v[122:125], v[148:151], v[16:31]
	v_cvt_pk_bf16_f32 v154, v68, v69
	v_add_f32_e32 v250, v95, v250
	v_add_f32_e32 v250, v64, v250
	v_mfma_f32_32x32x16_bf16 v[0:15], v[196:199], v[148:151], v[0:15]
	v_cvt_pk_bf16_f32 v155, v70, v71
	v_add_f32_e32 v250, v65, v250
	v_add_f32_e32 v250, v66, v250
	v_add_u32_e32 v126, s0, v184
	ds_read_b128 v[114:117], v126 offset:16384
	ds_read_b128 v[118:121], v126 offset:20480
	ds_read_b128 v[122:125], v126 offset:24576
	ds_read_b128 v[196:199], v126 offset:28672
	v_add_u32_e32 v248, s67, v177
	ds_read_b128 v[200:203], v248
	ds_read_b128 v[204:207], v248 offset:8192
	v_add_u32_e32 v249, s67, v178
	ds_read_b128 v[208:211], v249
	ds_read_b128 v[212:215], v249 offset:8192
	s_waitcnt lgkmcnt(8)
	v_mfma_f32_32x32x16_bf16 v[48:63], v[98:101], v[152:155], v[48:63]
	v_cvt_pk_bf16_f32 v156, v72, v73
	v_add_f32_e32 v250, v67, v250
	v_add_f32_e32 v250, v68, v250
	v_mfma_f32_32x32x16_bf16 v[32:47], v[102:105], v[152:155], v[32:47]
	v_cvt_pk_bf16_f32 v157, v74, v75
	v_add_f32_e32 v250, v69, v250
	v_add_f32_e32 v250, v70, v250
	v_mfma_f32_32x32x16_bf16 v[16:31], v[106:109], v[152:155], v[16:31]
	v_cvt_pk_bf16_f32 v158, v76, v77
	v_add_f32_e32 v250, v71, v250
	v_add_f32_e32 v250, v72, v250
	v_mfma_f32_32x32x16_bf16 v[0:15], v[110:113], v[152:155], v[0:15]
	v_cvt_pk_bf16_f32 v159, v78, v79
	v_add_f32_e32 v250, v73, v250
	v_add_f32_e32 v250, v74, v250
	v_add_u32_e32 v248, s67, v179
	ds_read_b128 v[216:219], v248
	ds_read_b128 v[220:223], v248 offset:8192
	v_add_u32_e32 v249, s67, v180
	ds_read_b128 v[224:227], v249
	ds_read_b128 v[228:231], v249 offset:8192
	s_waitcnt lgkmcnt(8)
	v_mfma_f32_32x32x16_bf16 v[48:63], v[114:117], v[156:159], v[48:63]
	v_add_f32_e32 v250, v75, v250
	v_add_f32_e32 v250, v76, v250
	v_mfma_f32_32x32x16_bf16 v[32:47], v[118:121], v[156:159], v[32:47]
	v_add_f32_e32 v250, v77, v250
	v_add_f32_e32 v250, v78, v250
	v_mfma_f32_32x32x16_bf16 v[16:31], v[122:125], v[156:159], v[16:31]
	v_add_f32_e32 v250, v79, v250
	v_mfma_f32_32x32x16_bf16 v[0:15], v[196:199], v[156:159], v[0:15]
	v_add_f32_e32 v181, v181, v250
	s_setprio 0
.LBB0_386:
	s_add_i32 s0, s62, 0x102
	s_cmp_ge_u32 s0, s16
	s_cbranch_scc1 .LBB0_377
	s_setprio 2
	s_waitcnt lgkmcnt(0)
	v_mfma_f32_32x32x16_bf16 v[80:95], v[200:203], v[128:131], v[232:247]
	v_mfma_f32_32x32x16_bf16 v[64:79], v[204:207], v[128:131], v[232:247]
	v_mfma_f32_32x32x16_bf16 v[80:95], v[208:211], v[132:135], v[80:95]
	v_mfma_f32_32x32x16_bf16 v[64:79], v[212:215], v[132:135], v[64:79]
	v_mfma_f32_32x32x16_bf16 v[80:95], v[216:219], v[136:139], v[80:95]
	v_mfma_f32_32x32x16_bf16 v[64:79], v[220:223], v[136:139], v[64:79]
	v_mfma_f32_32x32x16_bf16 v[80:95], v[224:227], v[140:143], v[80:95]
	v_mfma_f32_32x32x16_bf16 v[64:79], v[228:231], v[140:143], v[64:79]
	s_setprio 0
	s_branch .LBB0_377
